# attention: per-tile alpha=1 move removed (rescale path scales l itself); wave-role branches around the third K row chunk replaced by an exec mask
# baseline (speedup 1.0000x reference)
; __device__ __forceinline__ int ltid() { int t = threadIdx.x; asm volatile("" : "+v"(t)); return t; }
; #define SLOAD(i, k0) do { sr_[i].vs = *(const u32x4*)(vsrc + (k0)); \
;     { const unsigned char* kt_ = Kh + (size_t)(k0) * 192; sr_[i].ks0 = *(const u32x4*)(kt_ + tid * 16); if (k2) sr_[i].ks1 = *(const u32x4*)(kt_ + 8192 + tid * 16); } } while (0)
; __device__ __forceinline__ void attn_body(const unsigned char* __restrict__ Qb, const unsigned char* __restrict__ Kh, const unsigned char* __restrict__ Vt,
;                                           bf16_t* __restrict__ Ob, int seq, char* lds) {
;   const int tid = ltid(), wid = tid >> 6, lane = tid & 63, r32 = lane & 31, hi = lane >> 5;
;   unsigned char* V_lds = (unsigned char*)lds; unsigned char* K_lds = (unsigned char*)(lds + 3 * SHM_V);
;   float* ws = (float*)(lds + 3 * SHM_V + 3 * SHM_K) + wid * 64; float* li_l = ws; float* al_l = ws + 32;
;   float m_reg = -1e30f, l_reg = 0; f32x16 o[4] = {}; i32x8 qr[3];
;   const unsigned char* Qw = Qb + (long)(wid * QBLK + r32) * 192 + hi * 32;
; #pragma unroll
;   for (int m = 0; m < 3; ++m) { const u32x4 a0 = *reinterpret_cast<const u32x4*>(Qw + m * 64), a1 = *reinterpret_cast<const u32x4*>(Qw + m * 64 + 16);
;     qr[m] = (i32x8){(int)a0.x, (int)a0.y, (int)a0.z, (int)a0.w, (int)a1.x, (int)a1.y, (int)a1.z, (int)a1.w}; }
;   const unsigned char* vsrc = Vt + (size_t)(tid >> 2) * S_ + (tid & 3) * 16;
;   const int vw = (tid >> 2) * 80 + ((tid & 3) >> 1) * 16 + (tid & 1) * 8;
;   const int kw0 = KSWZ(tid / 12, (tid % 12) * 16), kw1 = KSWZ((tid + 512) / 12, ((tid + 512) % 12) * 16);
;   const bool k2 = tid < 256;
;   struct { u32x4 vs, ks0, ks1; } sr_[SDEPTH];
;     ...
;   f32x16 pA0, pA1, pB0, pB1; float mnA, mnB, alA, alB; i32x8 pa; const int NT = seq / KVBLK;
;     ...
;   int sP = 0, sC = 1, sN = 2;
;   SLOAD(0, 0); asm volatile("s_waitcnt vmcnt(0)" ::: "memory"); SWRITE(0, 0); SLOAD(0, KVBLK); __syncthreads();
;   asm volatile("s_waitcnt vmcnt(0)" ::: "memory"); SWRITE(1, 0); if (2 < NT) SLOAD(0, 2 * KVBLK);
.LBB0_260:
	s_and_b32 s26, s25, 7
	s_lshr_b32 s0, s25, 3
	v_readlane_b32 s2, v254, 6
	v_readlane_b32 s3, v254, 7
	s_lshl_b32 s1, s26, 13
	s_lshl_b32 s4, s0, 8
	s_add_u32 s1, s1, s4
	s_mul_i32 s1, s1, 0xc0
	s_add_u32 s14, s2, s1
	s_addc_u32 s15, s3, 0
	s_add_u32 s14, s14, 0x2a925800
	s_addc_u32 s15, s15, 0
	s_mul_i32 s1, s26, 0x180000
	s_add_u32 s8, s2, s1
	s_addc_u32 s9, s3, 0
	s_add_u32 s8, s8, 0x2c125800
	s_addc_u32 s9, s9, 0
	s_lshl_b32 s1, s26, 20
	s_add_u32 s10, s2, s1
	s_addc_u32 s11, s3, 0
	s_add_u32 s10, s10, 0x2d925800
	s_addc_u32 s11, s11, 0
	s_lshl_b32 s1, s0, 20
	s_lshl_b32 s4, s26, 8
	s_add_u32 s1, s1, s4
	s_add_u32 s1, s1, 0x800
	s_add_u32 s16, s2, s1
	s_addc_u32 s17, s3, 0
	s_add_u32 s16, s16, 0x1d200000
	s_addc_u32 s17, s17, 0
	v_lshrrev_b32_e32 v231, 6, v192
	v_and_b32_e32 v201, 31, v192
	v_readfirstlane_b32 s12, v231
	s_cmp_lt_u32 s12, 4
	s_cselect_b64 s[18:19], -1, 0
	v_bfe_u32 v229, v192, 5, 1
	v_lshl_or_b32 v224, v231, 5, v201
	v_mul_u32_u24_e32 v224, 0xc0, v224
	v_lshl_add_u32 v224, v229, 5, v224
	global_load_dwordx4 v[96:99], v224, s[14:15] offset:0
	global_load_dwordx4 v[100:103], v224, s[14:15] offset:16
	global_load_dwordx4 v[104:107], v224, s[14:15] offset:64
	global_load_dwordx4 v[108:111], v224, s[14:15] offset:80
	global_load_dwordx4 v[112:115], v224, s[14:15] offset:128
	global_load_dwordx4 v[116:119], v224, s[14:15] offset:144
	v_lshlrev_b32_e32 v214, 4, v192
	v_add_u32_e32 v215, 0x2000, v214
	v_lshrrev_b32_e32 v225, 2, v192
	v_and_b32_e32 v228, 3, v192
	v_lshlrev_b32_e32 v216, 13, v225
	v_lshl_add_u32 v216, v228, 4, v216
	global_load_dwordx4 v[202:205], v216, s[10:11]
	global_load_dwordx4 v[206:209], v214, s[8:9]
	s_mov_b64 exec, s[18:19]
	global_load_dwordx4 v[210:213], v215, s[8:9]
	s_mov_b64 exec, -1
	s_add_u32 s8, s8, 0x3000
	s_addc_u32 s9, s9, 0
	s_add_u32 s10, s10, 64
	s_addc_u32 s11, s11, 0
	global_load_dwordx4 v[128:131], v216, s[10:11]
	global_load_dwordx4 v[132:135], v214, s[8:9]
	s_mov_b64 exec, s[18:19]
	global_load_dwordx4 v[136:139], v215, s[8:9]
	s_mov_b64 exec, -1
	s_add_u32 s8, s8, 0x3000
	s_addc_u32 s9, s9, 0
	s_add_u32 s10, s10, 64
	s_addc_u32 s11, s11, 0
	global_load_dwordx4 v[140:143], v216, s[10:11]
	global_load_dwordx4 v[144:147], v214, s[8:9]
	s_mov_b64 exec, s[18:19]
	global_load_dwordx4 v[148:151], v215, s[8:9]
	s_mov_b64 exec, -1
	s_add_u32 s8, s8, 0x3000
	s_addc_u32 s9, s9, 0
	s_add_u32 s10, s10, 64
	s_addc_u32 s11, s11, 0
	v_mul_u32_u24_e32 v217, 0x50, v225
	v_lshrrev_b32_e32 v230, 1, v228
	v_lshl_add_u32 v217, v230, 4, v217
	v_and_b32_e32 v230, 1, v192
	v_lshl_add_u32 v217, v230, 3, v217
	s_mov_b32 s0, 0x2aaaaaab
	v_mul_hi_u32 v230, v192, s0
	v_lshrrev_b32_e32 v230, 1, v230
	v_add_lshl_u32 v218, v230, v192, 4
	v_add_u32_e32 v226, 0x200, v192
	v_mul_hi_u32 v230, v226, s0
	v_lshrrev_b32_e32 v230, 1, v230
	v_add_lshl_u32 v219, v230, v226, 4
	v_mul_u32_u24_e32 v220, 0xd0, v201
	v_lshl_add_u32 v220, v229, 5, v220
	v_add_u32_e32 v220, 40960, v220
	v_add_u32_e32 v218, 40960, v218
	v_add_u32_e32 v219, 40960, v219
	v_mul_u32_u24_e32 v221, 0x50, v201
	v_lshl_add_u32 v221, v229, 5, v221
	v_lshlrev_b32_e32 v222, 8, v231
	v_add_u32_e32 v222, 0x17000, v222
	v_lshl_add_u32 v223, v229, 4, v222
	v_lshl_add_u32 v222, v201, 2, v222
	v_mov_b64_e32 v[0:1], 0
	v_mov_b64_e32 v[2:3], 0
	v_mov_b64_e32 v[4:5], 0
	v_mov_b64_e32 v[6:7], 0
	v_mov_b64_e32 v[8:9], 0
	v_mov_b64_e32 v[10:11], 0
	v_mov_b64_e32 v[12:13], 0
	v_mov_b64_e32 v[14:15], 0
	v_mov_b64_e32 v[16:17], 0
	v_mov_b64_e32 v[18:19], 0
	v_mov_b64_e32 v[20:21], 0
	v_mov_b64_e32 v[22:23], 0
	v_mov_b64_e32 v[24:25], 0
	v_mov_b64_e32 v[26:27], 0
	v_mov_b64_e32 v[28:29], 0
	v_mov_b64_e32 v[30:31], 0
	v_mov_b64_e32 v[32:33], 0
	v_mov_b64_e32 v[34:35], 0
	v_mov_b64_e32 v[36:37], 0
	v_mov_b64_e32 v[38:39], 0
	v_mov_b64_e32 v[40:41], 0
	v_mov_b64_e32 v[42:43], 0
	v_mov_b64_e32 v[44:45], 0
	v_mov_b64_e32 v[46:47], 0
	v_mov_b64_e32 v[48:49], 0
	v_mov_b64_e32 v[50:51], 0
	v_mov_b64_e32 v[52:53], 0
	v_mov_b64_e32 v[54:55], 0
	v_mov_b64_e32 v[56:57], 0
	v_mov_b64_e32 v[58:59], 0
	v_mov_b64_e32 v[60:61], 0
	v_mov_b64_e32 v[62:63], 0
	v_mov_b32_e32 v193, 0xf149f2ca
	v_mov_b32_e32 v194, 0
	s_mov_b32 s13, 0x40fc551e
	v_mov_b64_e32 v[160:161], 0
	v_mov_b64_e32 v[162:163], 0
	v_mov_b64_e32 v[164:165], 0
	v_mov_b64_e32 v[166:167], 0
	v_mov_b64_e32 v[168:169], 0
	v_mov_b64_e32 v[170:171], 0
	v_mov_b64_e32 v[172:173], 0
	v_mov_b64_e32 v[174:175], 0
	v_mov_b32_e32 v227, 0
	v_mov_b32_e32 v201, 0x7c7c7c7c
	s_waitcnt vmcnt(0)
	ds_write2_b32 v217, v202, v204 offset1:1
	ds_write2_b32 v217, v203, v205 offset0:8 offset1:9
	ds_write_b128 v218, v[206:209] offset:0
	s_mov_b64 exec, s[18:19]
	ds_write_b128 v219, v[210:213] offset:0
	s_mov_b64 exec, -1
	v_add_u32_e32 v224, 10240, v217
	v_add_u32_e32 v225, 20480, v217
	ds_write2_b32 v224, v128, v130 offset1:1
	ds_write2_b32 v224, v129, v131 offset0:8 offset1:9
	ds_write_b128 v218, v[132:135] offset:13312
	s_mov_b64 exec, s[18:19]
	ds_write_b128 v219, v[136:139] offset:13312
	s_mov_b64 exec, -1
	s_mov_b32 s7, 0
	s_cmp_lt_u32 s12, 4
	s_cbranch_scc1 .Latt_p5
	s_mov_b32 s7, 1

; __device__ __forceinline__ int ltid() { int t = threadIdx.x; asm volatile("" : "+v"(t)); return t; }
; __device__ __forceinline__ void qkt(f32x16& p0, f32x16& p1, const unsigned char* Ks, const i32x8* qr, int r32, int hi) {
;   p0 = f32x16{}; p1 = f32x16{};
; #pragma unroll
;   for (int m = 0; m < 3; ++m) { const int cb = m * 64 + hi * 32;
;     const u32x4 a0 = *reinterpret_cast<const u32x4*>(Ks + KSWZ(r32, cb)), a1 = *reinterpret_cast<const u32x4*>(Ks + KSWZ(r32, cb) + 16);
;     const u32x4 c0 = *reinterpret_cast<const u32x4*>(Ks + KSWZ(32 + r32, cb)), c1 = *reinterpret_cast<const u32x4*>(Ks + KSWZ(32 + r32, cb) + 16);
;     const i32x8 b0 = {(int)a0.x, (int)a0.y, (int)a0.z, (int)a0.w, (int)a1.x, (int)a1.y, (int)a1.z, (int)a1.w};
;     const i32x8 b1 = {(int)c0.x, (int)c0.y, (int)c0.z, (int)c0.w, (int)c1.x, (int)c1.y, (int)c1.z, (int)c1.w};
;     p0 = __builtin_amdgcn_mfma_scale_f32_32x32x64_f8f6f4(b0, qr[m], p0, 0, 0, 0, 0x7F7F7F7F, 0, 0x7F7F7F7F);
;     p1 = __builtin_amdgcn_mfma_scale_f32_32x32x64_f8f6f4(b1, qr[m], p1, 0, 0, 0, 0x7F7F7F7F, 0, 0x7F7F7F7F); }
; }
; __device__ __forceinline__ void pv_d0(f32x16* o, const unsigned char* Vs, const i32x8& pa, int r32, int hi) {
; #pragma unroll
;   for (int d0 = 0; d0 < 4; ++d0) { const unsigned char* vp = Vs + (32 * d0 + r32) * 80 + hi * 32;
;     const u32x4 a0 = *reinterpret_cast<const u32x4*>(vp), a1 = *reinterpret_cast<const u32x4*>(vp + 16);
;     const i32x8 vb = {(int)a0.x, (int)a0.y, (int)a0.z, (int)a0.w, (int)a1.x, (int)a1.y, (int)a1.z, (int)a1.w};
;     o[d0] = __builtin_amdgcn_mfma_scale_f32_32x32x64_f8f6f4(pa, vb, o[d0], 0, 0, 0, 0x7A7A7A7A, 0, 0x7F7F7F7F); }
; }
; __device__ __forceinline__ void attn_body(const unsigned char* __restrict__ Qb, const unsigned char* __restrict__ Kh, const unsigned char* __restrict__ Vt,
;                                           bf16_t* __restrict__ Ob, int seq, char* lds) {
;   const int tid = ltid(), wid = tid >> 6, lane = tid & 63, r32 = lane & 31, hi = lane >> 5;
;   unsigned char* V_lds = (unsigned char*)lds; unsigned char* K_lds = (unsigned char*)(lds + 3 * SHM_V);
;   float* ws = (float*)(lds + 3 * SHM_V + 3 * SHM_K) + wid * 64; float* li_l = ws; float* al_l = ws + 32;
;   float m_reg = -1e30f, l_reg = 0; f32x16 o[4] = {}; i32x8 qr[3];
;   const unsigned char* Qw = Qb + (long)(wid * QBLK + r32) * 192 + hi * 32;
; #pragma unroll
.Latt_loop:
	s_cmp_eq_u32 s6, 0
	s_cbranch_scc1 .Latt_m_first
	s_add_u32 s4, s6, 2
	ds_read_b128 v[176:179], v221 offset:30720
	ds_read_b128 v[180:183], v221 offset:30736
	ds_read_b128 v[184:187], v221 offset:33280
	ds_read_b128 v[188:191], v221 offset:33296
	s_waitcnt lgkmcnt(4)
	v_mfma_scale_f32_32x32x64_f8f6f4 v[64:79], v[128:135], v[96:103], v[160:175], v235, v201 op_sel_hi:[0,0,0]
	ds_read_b128 v[128:131], v220 offset:128
	ds_read_b128 v[132:135], v220 offset:144
	v_mfma_scale_f32_32x32x64_f8f6f4 v[80:95], v[136:143], v[96:103], v[160:175], v235, v201 op_sel_hi:[0,0,0]
	ds_read_b128 v[136:139], v220 offset:6784
	ds_read_b128 v[140:143], v220 offset:6800
	s_cmp_lt_u32 s4, 128
	s_cbranch_scc0 .Latt_ms0_nowr
	s_waitcnt vmcnt(0)
	ds_write2_b32 v225, v202, v204 offset1:1
	ds_write2_b32 v225, v203, v205 offset0:8 offset1:9
	ds_write_b128 v218, v[206:209] offset:26624
	s_mov_b64 exec, s[18:19]
	ds_write_b128 v219, v[210:213] offset:26624
	s_mov_b64 exec, -1
.Latt_ms0_nowr:
	v_mfma_scale_f32_32x32x64_f8f6f4 v[64:79], v[144:151], v[104:111], v[64:79], v235, v201 op_sel_hi:[0,0,0]
	ds_read_b128 v[144:147], v220 offset:13376
	ds_read_b128 v[148:151], v220 offset:13392
	v_mfma_scale_f32_32x32x64_f8f6f4 v[80:95], v[152:159], v[104:111], v[80:95], v235, v201 op_sel_hi:[0,0,0]
	ds_read_b128 v[152:155], v220 offset:20032
	ds_read_b128 v[156:159], v220 offset:20048
	s_cmp_lt_u32 s4, 127
	s_cbranch_scc0 .Latt_ms0_nold
	global_load_dwordx4 v[202:205], v216, s[10:11]
	global_load_dwordx4 v[206:209], v214, s[8:9]
	s_mov_b64 exec, s[18:19]
	global_load_dwordx4 v[210:213], v215, s[8:9]
	s_mov_b64 exec, -1
	s_add_u32 s8, s8, 0x3000
	s_addc_u32 s9, s9, 0
	s_add_u32 s10, s10, 64
	s_addc_u32 s11, s11, 0

; __device__ __forceinline__ void attn_body(const unsigned char* __restrict__ Qb, const unsigned char* __restrict__ Kh, const unsigned char* __restrict__ Vt,
;                                           bf16_t* __restrict__ Ob, int seq, char* lds) {
;     ...
;   f32x16 pA0, pA1, pB0, pB1; float mnA, mnB, alA, alB; i32x8 pa; const int NT = seq / KVBLK;
.Latt_m_first:
	s_add_u32 s4, s6, 2
	s_waitcnt lgkmcnt(0)
	v_mfma_scale_f32_32x32x64_f8f6f4 v[64:79], v[128:135], v[96:103], v[160:175], v235, v201 op_sel_hi:[0,0,0]
	ds_read_b128 v[128:131], v220 offset:128
	ds_read_b128 v[132:135], v220 offset:144
	v_mfma_scale_f32_32x32x64_f8f6f4 v[80:95], v[136:143], v[96:103], v[160:175], v235, v201 op_sel_hi:[0,0,0]
	ds_read_b128 v[136:139], v220 offset:6784
	ds_read_b128 v[140:143], v220 offset:6800
	s_cmp_lt_u32 s4, 128
	s_cbranch_scc0 .Latt_mf_nowr
	s_waitcnt vmcnt(0)
	ds_write2_b32 v225, v202, v204 offset1:1
	ds_write2_b32 v225, v203, v205 offset0:8 offset1:9
	ds_write_b128 v218, v[206:209] offset:26624
	s_mov_b64 exec, s[18:19]
	ds_write_b128 v219, v[210:213] offset:26624
	s_mov_b64 exec, -1

; __device__ __forceinline__ void partialSM(f32x16& p0, f32x16& p1, float& m_reg, float& mn, float& alpha) {
;     ...
;   if (__builtin_expect(__all(pmax - m_reg <= THR / SCALE), 1)) { mn = m_reg; alpha = 1.f; }
;   else { mn = fmaxf(m_reg, pmax); alpha = __builtin_amdgcn_exp2f((m_reg - mn) * C); m_reg = mn; }
;   float mnC = -mn * C + 5.f;
;   for (int r = 0; r < 16; ++r) p0[r] = fmaf(p0[r], C, mnC); for (int r = 0; r < 16; ++r) p1[r] = fmaf(p1[r], C, mnC);
;   for (int r = 0; r < 16; ++r) p0[r] = __builtin_amdgcn_exp2f(p0[r]);
; }
; __device__ __forceinline__ void finishSM(f32x16& p0, f32x16& p1, float alpha, float& l_reg, i32x8& pa) {
;   for (int r = 0; r < 16; ++r) p1[r] = __builtin_amdgcn_exp2f(p1[r]);
;   float ps = 0; for (int r = 0; r < 16; ++r) ps += p0[r]; for (int r = 0; r < 16; ++r) ps += p1[r];
;   { auto rr = __builtin_amdgcn_permlane32_swap(__float_as_uint(ps), __float_as_uint(ps), false, false);
;     ps = __uint_as_float(rr[0]) + __uint_as_float(rr[1]); }
;   l_reg = l_reg * alpha + ps;
.Latt_m_nobar_0:
	v_max3_f32 v228, v64, v65, v66
	v_max3_f32 v229, v80, v81, v82
	v_max3_f32 v228, v228, v67, v68
	v_max3_f32 v229, v229, v83, v84
	v_max3_f32 v228, v228, v69, v70
	v_max3_f32 v229, v229, v85, v86
	v_max3_f32 v228, v228, v71, v72
	v_max3_f32 v229, v229, v87, v88
	v_max3_f32 v228, v228, v73, v74
	v_max3_f32 v229, v229, v89, v90
	v_max3_f32 v228, v228, v75, v76
	v_max3_f32 v229, v229, v91, v92
	v_max3_f32 v228, v228, v77, v78
	v_max3_f32 v229, v229, v93, v94
	v_max3_f32 v228, v228, v79, v95
	v_max_f32_e32 v228, v228, v229
	s_mov_b32 s5, 0
	v_cmp_ge_f32_e32 vcc, s13, v228
	s_cmp_eq_u32 s6, 0
	s_cbranch_scc1 .Latt_rare
	s_cmp_eq_u64 vcc, exec
	s_cbranch_scc0 .Latt_rare
.Latt_rare_back_0:
	v_exp_f32_e32 v64, v64
	v_exp_f32_e32 v65, v65
	v_exp_f32_e32 v66, v66
	v_exp_f32_e32 v67, v67
	v_add_f32_e32 v230, v64, v65
	v_exp_f32_e32 v68, v68
	v_add_f32_e32 v230, v66, v230
	v_exp_f32_e32 v69, v69
	v_cvt_pk_fp8_f32 v120, v64, v65
	v_add_f32_e32 v230, v67, v230
	v_exp_f32_e32 v70, v70
	v_add_f32_e32 v230, v68, v230
	v_exp_f32_e32 v71, v71
	v_cvt_pk_fp8_f32 v120, v66, v67 op_sel:[0,0,1]
	v_add_f32_e32 v230, v69, v230
	v_exp_f32_e32 v72, v72
	v_add_f32_e32 v230, v70, v230
	v_exp_f32_e32 v73, v73
	v_cvt_pk_fp8_f32 v121, v68, v69
	v_add_f32_e32 v230, v71, v230
	v_exp_f32_e32 v74, v74
	v_add_f32_e32 v230, v72, v230
	v_exp_f32_e32 v75, v75
	v_cvt_pk_fp8_f32 v121, v70, v71 op_sel:[0,0,1]
	v_add_f32_e32 v230, v73, v230
	v_exp_f32_e32 v76, v76
	v_add_f32_e32 v230, v74, v230
	v_exp_f32_e32 v77, v77
	v_cvt_pk_fp8_f32 v122, v72, v73
	v_add_f32_e32 v230, v75, v230
	v_exp_f32_e32 v78, v78
	v_add_f32_e32 v230, v76, v230
	v_exp_f32_e32 v79, v79
	v_cvt_pk_fp8_f32 v122, v74, v75 op_sel:[0,0,1]
	v_add_f32_e32 v230, v77, v230
	v_exp_f32_e32 v80, v80
	v_add_f32_e32 v230, v78, v230
	v_exp_f32_e32 v81, v81
	v_cvt_pk_fp8_f32 v123, v76, v77
	v_add_f32_e32 v230, v79, v230
	v_exp_f32_e32 v82, v82
	v_add_f32_e32 v230, v80, v230
	v_exp_f32_e32 v83, v83
	v_cvt_pk_fp8_f32 v123, v78, v79 op_sel:[0,0,1]
	v_add_f32_e32 v230, v81, v230
	v_exp_f32_e32 v84, v84
	v_add_f32_e32 v230, v82, v230
	v_exp_f32_e32 v85, v85
	v_cvt_pk_fp8_f32 v124, v80, v81
	v_add_f32_e32 v230, v83, v230
	v_exp_f32_e32 v86, v86
	v_add_f32_e32 v230, v84, v230
	v_exp_f32_e32 v87, v87
	v_cvt_pk_fp8_f32 v124, v82, v83 op_sel:[0,0,1]
	v_add_f32_e32 v230, v85, v230
	v_exp_f32_e32 v88, v88
	v_add_f32_e32 v230, v86, v230
	v_exp_f32_e32 v89, v89
	v_cvt_pk_fp8_f32 v125, v84, v85
	v_add_f32_e32 v230, v87, v230
	v_exp_f32_e32 v90, v90
	v_add_f32_e32 v230, v88, v230
	v_exp_f32_e32 v91, v91
	v_cvt_pk_fp8_f32 v125, v86, v87 op_sel:[0,0,1]
	v_add_f32_e32 v230, v89, v230
	v_exp_f32_e32 v92, v92
	v_add_f32_e32 v230, v90, v230
	v_exp_f32_e32 v93, v93
	v_cvt_pk_fp8_f32 v126, v88, v89
	v_add_f32_e32 v230, v91, v230
	v_exp_f32_e32 v94, v94
	v_add_f32_e32 v230, v92, v230
	v_exp_f32_e32 v95, v95
	v_cvt_pk_fp8_f32 v126, v90, v91 op_sel:[0,0,1]
	v_add_f32_e32 v230, v93, v230
	v_add_f32_e32 v230, v94, v230
	v_cvt_pk_fp8_f32 v127, v92, v93
	v_add_f32_e32 v230, v95, v230
	v_cvt_pk_fp8_f32 v127, v94, v95 op_sel:[0,0,1]
	v_add_f32_e32 v194, v194, v230
	s_waitcnt lgkmcnt(0)
	s_cmp_eq_u32 s7, 0
	s_cbranch_scc0 .Latt_v_nobar_0
	s_barrier
.Latt_v_nobar_0:
	s_add_u32 s6, s6, 1
	s_add_u32 s4, s6, 2
	ds_read_b128 v[176:179], v221 offset:0
	ds_read_b128 v[180:183], v221 offset:16
	ds_read_b128 v[184:187], v221 offset:2560
	ds_read_b128 v[188:191], v221 offset:2576
	s_waitcnt lgkmcnt(4)
	v_mfma_scale_f32_32x32x64_f8f6f4 v[64:79], v[128:135], v[96:103], v[160:175], v235, v201 op_sel_hi:[0,0,0]
	ds_read_b128 v[128:131], v220 offset:13440
	ds_read_b128 v[132:135], v220 offset:13456
	v_mfma_scale_f32_32x32x64_f8f6f4 v[80:95], v[136:143], v[96:103], v[160:175], v235, v201 op_sel_hi:[0,0,0]
	ds_read_b128 v[136:139], v220 offset:20096
	ds_read_b128 v[140:143], v220 offset:20112
	s_cmp_lt_u32 s4, 128
	s_cbranch_scc0 .Latt_ms1_nowr
	v_add_u32_e32 v228, 30720, v217
	s_waitcnt vmcnt(0)
	ds_write2_b32 v228, v202, v204 offset1:1
	ds_write2_b32 v228, v203, v205 offset0:8 offset1:9
	ds_write_b128 v218, v[206:209] offset:39936
	s_mov_b64 exec, s[18:19]
	ds_write_b128 v219, v[210:213] offset:39936
	s_mov_b64 exec, -1
.Latt_ms1_nowr:
	v_mfma_scale_f32_32x32x64_f8f6f4 v[64:79], v[144:151], v[104:111], v[64:79], v235, v201 op_sel_hi:[0,0,0]
	ds_read_b128 v[144:147], v220 offset:26688
	ds_read_b128 v[148:151], v220 offset:26704
	v_mfma_scale_f32_32x32x64_f8f6f4 v[80:95], v[152:159], v[104:111], v[80:95], v235, v201 op_sel_hi:[0,0,0]
	ds_read_b128 v[152:155], v220 offset:33344
	ds_read_b128 v[156:159], v220 offset:33360
	s_cmp_lt_u32 s4, 127
	s_cbranch_scc0 .Latt_ms1_nold
	global_load_dwordx4 v[202:205], v216, s[10:11]
	global_load_dwordx4 v[206:209], v214, s[8:9]
	s_mov_b64 exec, s[18:19]
	global_load_dwordx4 v[210:213], v215, s[8:9]
	s_mov_b64 exec, -1
	s_add_u32 s8, s8, 0x3000
	s_addc_u32 s9, s9, 0
	s_add_u32 s10, s10, 64
	s_addc_u32 s11, s11, 0

; __device__ __forceinline__ void partialSM(f32x16& p0, f32x16& p1, float& m_reg, float& mn, float& alpha) {
;   constexpr float C = SCALE * 1.4426950408889634f;
;   float pmax = p0[0]; for (int r = 1; r < 16; ++r) pmax = fmaxf(pmax, p0[r]); for (int r = 0; r < 16; ++r) pmax = fmaxf(pmax, p1[r]);
;   { auto rr = __builtin_amdgcn_permlane32_swap(__float_as_uint(pmax), __float_as_uint(pmax), false, false);
;     pmax = fmaxf(__uint_as_float(rr[0]), __uint_as_float(rr[1])); }
;   if (__builtin_expect(__all(pmax - m_reg <= THR / SCALE), 1)) { mn = m_reg; alpha = 1.f; }
;   else { mn = fmaxf(m_reg, pmax); alpha = __builtin_amdgcn_exp2f((m_reg - mn) * C); m_reg = mn; }
.Latt_m_nobar_1:
	v_max3_f32 v228, v64, v65, v66
	v_max3_f32 v229, v80, v81, v82
	v_max3_f32 v228, v228, v67, v68
	v_max3_f32 v229, v229, v83, v84
	v_max3_f32 v228, v228, v69, v70
	v_max3_f32 v229, v229, v85, v86
	v_max3_f32 v228, v228, v71, v72
	v_max3_f32 v229, v229, v87, v88
	v_max3_f32 v228, v228, v73, v74
	v_max3_f32 v229, v229, v89, v90
	v_max3_f32 v228, v228, v75, v76
	v_max3_f32 v229, v229, v91, v92
	v_max3_f32 v228, v228, v77, v78
	v_max3_f32 v229, v229, v93, v94
	v_max3_f32 v228, v228, v79, v95
	v_max_f32_e32 v228, v228, v229
	s_mov_b32 s5, 1
	v_cmp_ge_f32_e32 vcc, s13, v228
	s_cmp_eq_u64 vcc, exec
	s_cbranch_scc0 .Latt_rare

; __device__ __forceinline__ int ltid() { int t = threadIdx.x; asm volatile("" : "+v"(t)); return t; }
; __device__ __forceinline__ void qkt(f32x16& p0, f32x16& p1, const unsigned char* Ks, const i32x8* qr, int r32, int hi) {
;   p0 = f32x16{}; p1 = f32x16{};
; #pragma unroll
;   for (int m = 0; m < 3; ++m) { const int cb = m * 64 + hi * 32;
;     const u32x4 a0 = *reinterpret_cast<const u32x4*>(Ks + KSWZ(r32, cb)), a1 = *reinterpret_cast<const u32x4*>(Ks + KSWZ(r32, cb) + 16);
;     const u32x4 c0 = *reinterpret_cast<const u32x4*>(Ks + KSWZ(32 + r32, cb)), c1 = *reinterpret_cast<const u32x4*>(Ks + KSWZ(32 + r32, cb) + 16);
;     const i32x8 b0 = {(int)a0.x, (int)a0.y, (int)a0.z, (int)a0.w, (int)a1.x, (int)a1.y, (int)a1.z, (int)a1.w};
;     const i32x8 b1 = {(int)c0.x, (int)c0.y, (int)c0.z, (int)c0.w, (int)c1.x, (int)c1.y, (int)c1.z, (int)c1.w};
;     p0 = __builtin_amdgcn_mfma_scale_f32_32x32x64_f8f6f4(b0, qr[m], p0, 0, 0, 0, 0x7F7F7F7F, 0, 0x7F7F7F7F);
;     p1 = __builtin_amdgcn_mfma_scale_f32_32x32x64_f8f6f4(b1, qr[m], p1, 0, 0, 0, 0x7F7F7F7F, 0, 0x7F7F7F7F); }
; }
; __device__ __forceinline__ void pv_d0(f32x16* o, const unsigned char* Vs, const i32x8& pa, int r32, int hi) {
; #pragma unroll
;   for (int d0 = 0; d0 < 4; ++d0) { const unsigned char* vp = Vs + (32 * d0 + r32) * 80 + hi * 32;
;     const u32x4 a0 = *reinterpret_cast<const u32x4*>(vp), a1 = *reinterpret_cast<const u32x4*>(vp + 16);
;     const i32x8 vb = {(int)a0.x, (int)a0.y, (int)a0.z, (int)a0.w, (int)a1.x, (int)a1.y, (int)a1.z, (int)a1.w};
;     o[d0] = __builtin_amdgcn_mfma_scale_f32_32x32x64_f8f6f4(pa, vb, o[d0], 0, 0, 0, 0x7A7A7A7A, 0, 0x7F7F7F7F); }
; }
; __device__ __forceinline__ void attn_body(const unsigned char* __restrict__ Qb, const unsigned char* __restrict__ Kh, const unsigned char* __restrict__ Vt,
;                                           bf16_t* __restrict__ Ob, int seq, char* lds) {
;   const int tid = ltid(), wid = tid >> 6, lane = tid & 63, r32 = lane & 31, hi = lane >> 5;
;   unsigned char* V_lds = (unsigned char*)lds; unsigned char* K_lds = (unsigned char*)(lds + 3 * SHM_V);
;   float* ws = (float*)(lds + 3 * SHM_V + 3 * SHM_K) + wid * 64; float* li_l = ws; float* al_l = ws + 32;
;   float m_reg = -1e30f, l_reg = 0; f32x16 o[4] = {}; i32x8 qr[3];
;   const unsigned char* Qw = Qb + (long)(wid * QBLK + r32) * 192 + hi * 32;
; #pragma unroll
.Latt_v_nobar_1:
	s_add_u32 s6, s6, 1
	s_add_u32 s4, s6, 2
	ds_read_b128 v[176:179], v221 offset:10240
	ds_read_b128 v[180:183], v221 offset:10256
	ds_read_b128 v[184:187], v221 offset:12800
	ds_read_b128 v[188:191], v221 offset:12816
	s_waitcnt lgkmcnt(4)
	v_mfma_scale_f32_32x32x64_f8f6f4 v[64:79], v[128:135], v[96:103], v[160:175], v235, v201 op_sel_hi:[0,0,0]
	ds_read_b128 v[128:131], v220 offset:26752
	ds_read_b128 v[132:135], v220 offset:26768
	v_mfma_scale_f32_32x32x64_f8f6f4 v[80:95], v[136:143], v[96:103], v[160:175], v235, v201 op_sel_hi:[0,0,0]
	ds_read_b128 v[136:139], v220 offset:33408
	ds_read_b128 v[140:143], v220 offset:33424
	s_cmp_lt_u32 s4, 128
	s_cbranch_scc0 .Latt_ms2_nowr
	s_waitcnt vmcnt(0)
	ds_write2_b32 v217, v202, v204 offset1:1
	ds_write2_b32 v217, v203, v205 offset0:8 offset1:9
	ds_write_b128 v218, v[206:209] offset:0
	s_mov_b64 exec, s[18:19]
	ds_write_b128 v219, v[210:213] offset:0
	s_mov_b64 exec, -1
.Latt_ms2_nowr:
	v_mfma_scale_f32_32x32x64_f8f6f4 v[64:79], v[144:151], v[104:111], v[64:79], v235, v201 op_sel_hi:[0,0,0]
	ds_read_b128 v[144:147], v220 offset:40000
	ds_read_b128 v[148:151], v220 offset:40016
	v_mfma_scale_f32_32x32x64_f8f6f4 v[80:95], v[152:159], v[104:111], v[80:95], v235, v201 op_sel_hi:[0,0,0]
	ds_read_b128 v[152:155], v220 offset:46656
	ds_read_b128 v[156:159], v220 offset:46672
	s_cmp_lt_u32 s4, 127
	s_cbranch_scc0 .Latt_ms2_nold
	global_load_dwordx4 v[202:205], v216, s[10:11]
	global_load_dwordx4 v[206:209], v214, s[8:9]
	s_mov_b64 exec, s[18:19]
	global_load_dwordx4 v[210:213], v215, s[8:9]
	s_mov_b64 exec, -1
	s_add_u32 s8, s8, 0x3000
	s_addc_u32 s9, s9, 0
	s_add_u32 s10, s10, 64
	s_addc_u32 s11, s11, 0

; __device__ __forceinline__ void partialSM(f32x16& p0, f32x16& p1, float& m_reg, float& mn, float& alpha) {
;   constexpr float C = SCALE * 1.4426950408889634f;
;   float pmax = p0[0]; for (int r = 1; r < 16; ++r) pmax = fmaxf(pmax, p0[r]); for (int r = 0; r < 16; ++r) pmax = fmaxf(pmax, p1[r]);
;   { auto rr = __builtin_amdgcn_permlane32_swap(__float_as_uint(pmax), __float_as_uint(pmax), false, false);
;     pmax = fmaxf(__uint_as_float(rr[0]), __uint_as_float(rr[1])); }
;   if (__builtin_expect(__all(pmax - m_reg <= THR / SCALE), 1)) { mn = m_reg; alpha = 1.f; }
;   else { mn = fmaxf(m_reg, pmax); alpha = __builtin_amdgcn_exp2f((m_reg - mn) * C); m_reg = mn; }
.Latt_m_nobar_2:
	v_max3_f32 v228, v64, v65, v66
	v_max3_f32 v229, v80, v81, v82
	v_max3_f32 v228, v228, v67, v68
	v_max3_f32 v229, v229, v83, v84
	v_max3_f32 v228, v228, v69, v70
	v_max3_f32 v229, v229, v85, v86
	v_max3_f32 v228, v228, v71, v72
	v_max3_f32 v229, v229, v87, v88
	v_max3_f32 v228, v228, v73, v74
	v_max3_f32 v229, v229, v89, v90
	v_max3_f32 v228, v228, v75, v76
	v_max3_f32 v229, v229, v91, v92
	v_max3_f32 v228, v228, v77, v78
	v_max3_f32 v229, v229, v93, v94
	v_max3_f32 v228, v228, v79, v95
	v_max_f32_e32 v228, v228, v229
	s_mov_b32 s5, 2
	v_cmp_ge_f32_e32 vcc, s13, v228
	s_cmp_eq_u64 vcc, exec
	s_cbranch_scc0 .Latt_rare

; __device__ __forceinline__ int ltid() { int t = threadIdx.x; asm volatile("" : "+v"(t)); return t; }
; __device__ __forceinline__ void qkt(f32x16& p0, f32x16& p1, const unsigned char* Ks, const i32x8* qr, int r32, int hi) {
;   p0 = f32x16{}; p1 = f32x16{};
; #pragma unroll
;   for (int m = 0; m < 3; ++m) { const int cb = m * 64 + hi * 32;
;     const u32x4 a0 = *reinterpret_cast<const u32x4*>(Ks + KSWZ(r32, cb)), a1 = *reinterpret_cast<const u32x4*>(Ks + KSWZ(r32, cb) + 16);
;     const u32x4 c0 = *reinterpret_cast<const u32x4*>(Ks + KSWZ(32 + r32, cb)), c1 = *reinterpret_cast<const u32x4*>(Ks + KSWZ(32 + r32, cb) + 16);
;     const i32x8 b0 = {(int)a0.x, (int)a0.y, (int)a0.z, (int)a0.w, (int)a1.x, (int)a1.y, (int)a1.z, (int)a1.w};
;     const i32x8 b1 = {(int)c0.x, (int)c0.y, (int)c0.z, (int)c0.w, (int)c1.x, (int)c1.y, (int)c1.z, (int)c1.w};
;     p0 = __builtin_amdgcn_mfma_scale_f32_32x32x64_f8f6f4(b0, qr[m], p0, 0, 0, 0, 0x7F7F7F7F, 0, 0x7F7F7F7F);
;     p1 = __builtin_amdgcn_mfma_scale_f32_32x32x64_f8f6f4(b1, qr[m], p1, 0, 0, 0, 0x7F7F7F7F, 0, 0x7F7F7F7F); }
; }
; __device__ __forceinline__ void pv_d0(f32x16* o, const unsigned char* Vs, const i32x8& pa, int r32, int hi) {
; #pragma unroll
;   for (int d0 = 0; d0 < 4; ++d0) { const unsigned char* vp = Vs + (32 * d0 + r32) * 80 + hi * 32;
;     const u32x4 a0 = *reinterpret_cast<const u32x4*>(vp), a1 = *reinterpret_cast<const u32x4*>(vp + 16);
;     const i32x8 vb = {(int)a0.x, (int)a0.y, (int)a0.z, (int)a0.w, (int)a1.x, (int)a1.y, (int)a1.z, (int)a1.w};
;     o[d0] = __builtin_amdgcn_mfma_scale_f32_32x32x64_f8f6f4(pa, vb, o[d0], 0, 0, 0, 0x7A7A7A7A, 0, 0x7F7F7F7F); }
; }
; __device__ __forceinline__ void attn_body(const unsigned char* __restrict__ Qb, const unsigned char* __restrict__ Kh, const unsigned char* __restrict__ Vt,
;                                           bf16_t* __restrict__ Ob, int seq, char* lds) {
;   const int tid = ltid(), wid = tid >> 6, lane = tid & 63, r32 = lane & 31, hi = lane >> 5;
;   unsigned char* V_lds = (unsigned char*)lds; unsigned char* K_lds = (unsigned char*)(lds + 3 * SHM_V);
;   float* ws = (float*)(lds + 3 * SHM_V + 3 * SHM_K) + wid * 64; float* li_l = ws; float* al_l = ws + 32;
;   float m_reg = -1e30f, l_reg = 0; f32x16 o[4] = {}; i32x8 qr[3];
;   const unsigned char* Qw = Qb + (long)(wid * QBLK + r32) * 192 + hi * 32;
; #pragma unroll
.Latt_v_nobar_2:
	s_add_u32 s6, s6, 1
	s_add_u32 s4, s6, 2
	ds_read_b128 v[176:179], v221 offset:20480
	ds_read_b128 v[180:183], v221 offset:20496
	ds_read_b128 v[184:187], v221 offset:23040
	ds_read_b128 v[188:191], v221 offset:23056
	s_waitcnt lgkmcnt(4)
	v_mfma_scale_f32_32x32x64_f8f6f4 v[64:79], v[128:135], v[96:103], v[160:175], v235, v201 op_sel_hi:[0,0,0]
	ds_read_b128 v[128:131], v220 offset:40064
	ds_read_b128 v[132:135], v220 offset:40080
	v_mfma_scale_f32_32x32x64_f8f6f4 v[80:95], v[136:143], v[96:103], v[160:175], v235, v201 op_sel_hi:[0,0,0]
	ds_read_b128 v[136:139], v220 offset:46720
	ds_read_b128 v[140:143], v220 offset:46736
	s_cmp_lt_u32 s4, 128
	s_cbranch_scc0 .Latt_ms3_nowr
	s_waitcnt vmcnt(0)
	ds_write2_b32 v224, v202, v204 offset1:1
	ds_write2_b32 v224, v203, v205 offset0:8 offset1:9
	ds_write_b128 v218, v[206:209] offset:13312
	s_mov_b64 exec, s[18:19]
	ds_write_b128 v219, v[210:213] offset:13312
	s_mov_b64 exec, -1
.Latt_ms3_nowr:
	v_mfma_scale_f32_32x32x64_f8f6f4 v[64:79], v[144:151], v[104:111], v[64:79], v235, v201 op_sel_hi:[0,0,0]
	ds_read_b128 v[144:147], v220 offset:64
	ds_read_b128 v[148:151], v220 offset:80
	v_mfma_scale_f32_32x32x64_f8f6f4 v[80:95], v[152:159], v[104:111], v[80:95], v235, v201 op_sel_hi:[0,0,0]
	ds_read_b128 v[152:155], v220 offset:6720
	ds_read_b128 v[156:159], v220 offset:6736
	s_cmp_lt_u32 s4, 127
	s_cbranch_scc0 .Latt_ms3_nold
	global_load_dwordx4 v[202:205], v216, s[10:11]
	global_load_dwordx4 v[206:209], v214, s[8:9]
	s_mov_b64 exec, s[18:19]
	global_load_dwordx4 v[210:213], v215, s[8:9]
	s_mov_b64 exec, -1
	s_add_u32 s8, s8, 0x3000
	s_addc_u32 s9, s9, 0
	s_add_u32 s10, s10, 64
	s_addc_u32 s11, s11, 0

; __device__ __forceinline__ void partialSM(f32x16& p0, f32x16& p1, float& m_reg, float& mn, float& alpha) {
;   constexpr float C = SCALE * 1.4426950408889634f;
;   float pmax = p0[0]; for (int r = 1; r < 16; ++r) pmax = fmaxf(pmax, p0[r]); for (int r = 0; r < 16; ++r) pmax = fmaxf(pmax, p1[r]);
;   { auto rr = __builtin_amdgcn_permlane32_swap(__float_as_uint(pmax), __float_as_uint(pmax), false, false);
;     pmax = fmaxf(__uint_as_float(rr[0]), __uint_as_float(rr[1])); }
;   if (__builtin_expect(__all(pmax - m_reg <= THR / SCALE), 1)) { mn = m_reg; alpha = 1.f; }
;   else { mn = fmaxf(m_reg, pmax); alpha = __builtin_amdgcn_exp2f((m_reg - mn) * C); m_reg = mn; }
.Latt_m_nobar_3:
	v_max3_f32 v228, v64, v65, v66
	v_max3_f32 v229, v80, v81, v82
	v_max3_f32 v228, v228, v67, v68
	v_max3_f32 v229, v229, v83, v84
	v_max3_f32 v228, v228, v69, v70
	v_max3_f32 v229, v229, v85, v86
	v_max3_f32 v228, v228, v71, v72
	v_max3_f32 v229, v229, v87, v88
	v_max3_f32 v228, v228, v73, v74
	v_max3_f32 v229, v229, v89, v90
	v_max3_f32 v228, v228, v75, v76
	v_max3_f32 v229, v229, v91, v92
	v_max3_f32 v228, v228, v77, v78
	v_max3_f32 v229, v229, v93, v94
	v_max3_f32 v228, v228, v79, v95
	v_max_f32_e32 v228, v228, v229
	s_mov_b32 s5, 3
	v_cmp_ge_f32_e32 vcc, s13, v228
	s_cmp_eq_u64 vcc, exec
	s_cbranch_scc0 .Latt_rare

; __device__ __forceinline__ void partialSM(f32x16& p0, f32x16& p1, float& m_reg, float& mn, float& alpha) {
;     ...
;   { auto rr = __builtin_amdgcn_permlane32_swap(__float_as_uint(pmax), __float_as_uint(pmax), false, false);
;     pmax = fmaxf(__uint_as_float(rr[0]), __uint_as_float(rr[1])); }
;   if (__builtin_expect(__all(pmax - m_reg <= THR / SCALE), 1)) { mn = m_reg; alpha = 1.f; }
;   else { mn = fmaxf(m_reg, pmax); alpha = __builtin_amdgcn_exp2f((m_reg - mn) * C); m_reg = mn; }
; __device__ __forceinline__ void finishSM(f32x16& p0, f32x16& p1, float alpha, float& l_reg, i32x8& pa) {
;     ...
;   l_reg = l_reg * alpha + ps;
.Latt_rare:
	v_mov_b32_e32 v229, v228
	s_nop 1
	v_permlane32_swap_b32_e32 v228, v229
	v_max_f32_e32 v228, v228, v229
	v_sub_f32_e32 v229, v228, v227
	v_max_f32_e32 v229, v193, v229
	v_sub_f32_e32 v231, v193, v229
	v_exp_f32_e32 v226, v231
	v_mov_b32_e32 v193, v229
	s_nop 0
	v_mul_f32_e32 v194, v194, v226
	v_sub_f32_e32 v231, v236, v229
	v_sub_f32_e32 v229, v231, v227
	v_mov_b32_e32 v227, v231
	v_add_f32_e32 v64, v64, v229
	v_add_f32_e32 v65, v65, v229
	v_add_f32_e32 v66, v66, v229
	v_add_f32_e32 v67, v67, v229
	v_add_f32_e32 v68, v68, v229
	v_add_f32_e32 v69, v69, v229
	v_add_f32_e32 v70, v70, v229
	v_add_f32_e32 v71, v71, v229
	v_add_f32_e32 v72, v72, v229
	v_add_f32_e32 v73, v73, v229
	v_add_f32_e32 v74, v74, v229
	v_add_f32_e32 v75, v75, v229
	v_add_f32_e32 v76, v76, v229
	v_add_f32_e32 v77, v77, v229
	v_add_f32_e32 v78, v78, v229
	v_add_f32_e32 v79, v79, v229
	v_add_f32_e32 v80, v80, v229
	v_add_f32_e32 v81, v81, v229
	v_add_f32_e32 v82, v82, v229
	v_add_f32_e32 v83, v83, v229
	v_add_f32_e32 v84, v84, v229
	v_add_f32_e32 v85, v85, v229
	v_add_f32_e32 v86, v86, v229
	v_add_f32_e32 v87, v87, v229
	v_add_f32_e32 v88, v88, v229
	v_add_f32_e32 v89, v89, v229
	v_add_f32_e32 v90, v90, v229
	v_add_f32_e32 v91, v91, v229
	v_add_f32_e32 v92, v92, v229
	v_add_f32_e32 v93, v93, v229
	v_add_f32_e32 v94, v94, v229
	v_add_f32_e32 v95, v95, v229
	v_mov_b32_e32 v160, v227
	v_mov_b32_e32 v161, v227
	v_mov_b32_e32 v162, v227
	v_mov_b32_e32 v163, v227
	v_mov_b32_e32 v164, v227
	v_mov_b32_e32 v165, v227
	v_mov_b32_e32 v166, v227
	v_mov_b32_e32 v167, v227
	v_mov_b32_e32 v168, v227
	v_mov_b32_e32 v169, v227
	v_mov_b32_e32 v170, v227
	v_mov_b32_e32 v171, v227
	v_mov_b32_e32 v172, v227
	v_mov_b32_e32 v173, v227
	v_mov_b32_e32 v174, v227
	v_mov_b32_e32 v175, v227
	s_mov_b32 exec_hi, 0
	ds_write_b32 v222, v226 offset:128
	s_mov_b64 exec, -1
	s_waitcnt lgkmcnt(0)
	ds_read_b128 v[176:179], v223 offset:128
	ds_read_b128 v[180:183], v223 offset:160
	ds_read_b128 v[184:187], v223 offset:192
	ds_read_b128 v[188:191], v223 offset:224
	s_waitcnt lgkmcnt(0)
	v_mul_f32_e32 v0, v0, v176
	v_mul_f32_e32 v1, v1, v177
	v_mul_f32_e32 v2, v2, v178
	v_mul_f32_e32 v3, v3, v179
	v_mul_f32_e32 v4, v4, v180
	v_mul_f32_e32 v5, v5, v181
	v_mul_f32_e32 v6, v6, v182
	v_mul_f32_e32 v7, v7, v183
	v_mul_f32_e32 v8, v8, v184
	v_mul_f32_e32 v9, v9, v185
	v_mul_f32_e32 v10, v10, v186
	v_mul_f32_e32 v11, v11, v187
	v_mul_f32_e32 v12, v12, v188
	v_mul_f32_e32 v13, v13, v189
	v_mul_f32_e32 v14, v14, v190
	v_mul_f32_e32 v15, v15, v191
	v_mul_f32_e32 v16, v16, v176
	v_mul_f32_e32 v17, v17, v177
	v_mul_f32_e32 v18, v18, v178
	v_mul_f32_e32 v19, v19, v179
	v_mul_f32_e32 v20, v20, v180
	v_mul_f32_e32 v21, v21, v181
	v_mul_f32_e32 v22, v22, v182
	v_mul_f32_e32 v23, v23, v183
	v_mul_f32_e32 v24, v24, v184
	v_mul_f32_e32 v25, v25, v185
	v_mul_f32_e32 v26, v26, v186
	v_mul_f32_e32 v27, v27, v187
	v_mul_f32_e32 v28, v28, v188
	v_mul_f32_e32 v29, v29, v189
	v_mul_f32_e32 v30, v30, v190
	v_mul_f32_e32 v31, v31, v191
	v_mul_f32_e32 v32, v32, v176
	v_mul_f32_e32 v33, v33, v177
	v_mul_f32_e32 v34, v34, v178
	v_mul_f32_e32 v35, v35, v179
	v_mul_f32_e32 v36, v36, v180
	v_mul_f32_e32 v37, v37, v181
	v_mul_f32_e32 v38, v38, v182
	v_mul_f32_e32 v39, v39, v183
	v_mul_f32_e32 v40, v40, v184
	v_mul_f32_e32 v41, v41, v185
	v_mul_f32_e32 v42, v42, v186
	v_mul_f32_e32 v43, v43, v187
	v_mul_f32_e32 v44, v44, v188
	v_mul_f32_e32 v45, v45, v189
	v_mul_f32_e32 v46, v46, v190
	v_mul_f32_e32 v47, v47, v191
	v_mul_f32_e32 v48, v48, v176
	v_mul_f32_e32 v49, v49, v177
	v_mul_f32_e32 v50, v50, v178
	v_mul_f32_e32 v51, v51, v179
	v_mul_f32_e32 v52, v52, v180
	v_mul_f32_e32 v53, v53, v181
	v_mul_f32_e32 v54, v54, v182
	v_mul_f32_e32 v55, v55, v183
	v_mul_f32_e32 v56, v56, v184
	v_mul_f32_e32 v57, v57, v185
	v_mul_f32_e32 v58, v58, v186
	v_mul_f32_e32 v59, v59, v187
	v_mul_f32_e32 v60, v60, v188
	v_mul_f32_e32 v61, v61, v189
	v_mul_f32_e32 v62, v62, v190
	v_mul_f32_e32 v63, v63, v191
	s_cmp_eq_u32 s5, 0
	s_cbranch_scc1 .Latt_rare_back_0
	s_cmp_eq_u32 s5, 1
	s_cbranch_scc1 .Latt_rare_back_1
	s_cmp_eq_u32 s5, 2
	s_cbranch_scc1 .Latt_rare_back_2
	s_branch .Latt_rare_back_3
